# attention: no static priority raise in either unit; diff K tile swizzle on row&15 (conflict-free b128 reads)
# speedup vs baseline: 1.0068x; 1.0068x over previous
; __device__ __forceinline__ int v_st(int k, int c) { const int kk = (k & ~0xC) | ((k & 4) << 1) | ((k & 8) >> 1); return ((kk >> 3) * 4 + (c >> 5)) * 512 + ((kk & 7) * 32 + (c & 31)) * 2; }
; __device__ __forceinline__ int v_rd_base(int lane) { return ((lane & 3) << 3) | (((lane >> 2) & 3) << 6) | (((lane >> 4) & 1) << 5) | (((lane >> 5) & 1) << 8); }
; #define SLOAD(i, k0) do { sr_[i].vs0 = ld8(&Vg[(long)((k0) + sr) * LDP + sc]); sr_[i].vs1 = ld8(&Vg[(long)((k0) + 32 + sr) * LDP + sc]); \
;     sr_[i].ks0 = ld8(&Kg[(long)((k0) + sr) * LDP + sc]); sr_[i].ks1 = ld8(&Kg[(long)((k0) + 32 + sr) * LDP + sc]); } while (0)
; #define SWRITE(off, i) do { *(bf16x8*)(V_lds + (off) + vst0) = sr_[i].vs0;          \
;     *(bf16x8*)(V_lds + (off) + vst1) = sr_[i].vs1; int kc = sc * 2;               \
;     *(bf16x8*)(K_lds + (off) + KSWZ(sr, kc)) = sr_[i].ks0;                       \
;     *(bf16x8*)(K_lds + (off) + KSWZ(32 + sr, kc)) = sr_[i].ks1; } while (0)
; template <int MODE, int ORD> ...
;     ...
;   const bf16* Qw = Qb + (long)(wq * 32 + r32) * LDP + cst * 64 + hi * 8;
; #pragma unroll
;   for (int d0 = 0; d0 < ND0; ++d0) qr[d0] = scale_bf16x8(ld8(Qw + d0 * 16), C);
;   const int qpos = qpos0 + wq * 32 + r32;
;   const int qw0 = qpos0 + wq * 32;
;   const int cboff = cst * 128;
;   int sr = tid >> 4, sc = (tid & 15) * 8, vst0 = v_st(sr, sc), vst1 = v_st(32 + sr, sc);
;   int vb0 = (int)(uintptr_t)V_lds + v_rd_base(lane);
;   const bf16* Kg = Kh + (long)kbeg * LDP; const bf16* Vg = Vh + (long)kbeg * LDP;
;   struct { bf16x8 vs0, vs1, ks0, ks1; } sr_[1];
;     ...
;   SLOAD(SE, 0); asm volatile("s_waitcnt vmcnt(0)" ::: "memory"); SWRITE(0, SE); __syncthreads();
.LBB0_157:
	s_or_b64 exec, exec, s[0:1]
	s_lshl_b32 s68, s6, 7
	s_add_u32 s6, s10, s68
	s_addc_u32 s7, s11, 0
	s_mul_i32 s0, s7, 0x2400
	s_mul_hi_u32 s1, s6, 0x2400
	s_add_i32 s1, s1, s0
	s_mul_i32 s0, s6, 0x2400
	s_add_u32 s0, s20, s0
	s_addc_u32 s1, s21, s1
	s_lshl_b32 s78, s80, 8
	s_add_u32 s0, s0, s78
	s_mul_i32 s18, s11, 0x2400
	s_mul_hi_u32 s19, s10, 0x2400
	s_addc_u32 s1, s1, 0
	s_add_i32 s19, s19, s18
	s_mul_i32 s18, s10, 0x2400
	s_add_u32 s18, s20, s18
	s_addc_u32 s19, s21, s19
	s_add_u32 s18, s18, s78
	s_addc_u32 s19, s19, 0
	s_add_u32 s42, s18, 0x1000
	s_addc_u32 s43, s19, 0
	s_and_b32 s66, s62, 3
	v_and_b32_e32 v184, 31, v40
	s_lshl_b32 s79, s66, 5
	v_or_b32_e32 v0, s79, v184
	v_mul_u32_u24_e32 v0, 0x1200, v0
	s_ashr_i32 s64, s63, 8
	v_lshlrev_b32_e32 v204, 1, v0
	v_lshl_add_u64 v[0:1], s[0:1], 0, v[204:205]
	s_lshl_b32 s0, s64, 6
	v_bfe_u32 v185, v40, 5, 1
	s_ashr_i32 s1, s0, 31
	v_lshl_add_u64 v[0:1], s[0:1], 1, v[0:1]
	v_lshlrev_b32_e32 v204, 4, v185
	v_lshl_add_u64 v[4:5], v[0:1], 0, v[204:205]
	global_load_dwordx4 v[0:3], v[4:5], off
	v_ashrrev_i32_e32 v38, 4, v40
	v_lshlrev_b32_e32 v16, 3, v40
	v_add_u32_e32 v17, 32, v38
	v_and_b32_e32 v41, 0x78, v16
	v_lshlrev_b32_e32 v19, 4, v40
	v_and_b32_e32 v20, 0xfffff0, v38
	v_lshlrev_b32_e32 v21, 1, v38
	v_lshrrev_b32_e32 v22, 1, v38
	v_and_b32_e32 v23, 3, v38
	v_and_b32_e32 v47, 0xf0, v19
	v_and_or_b32 v19, v21, 8, v20
	v_and_or_b32 v20, v22, 4, v23
	v_and_b32_e32 v22, 0xfffff0, v17
	v_lshlrev_b32_e32 v23, 1, v17
	v_and_b32_e32 v18, 0xf0, v40
	v_bfe_u32 v16, v16, 5, 2
	v_lshlrev_b32_e32 v24, 8, v38
	v_lshlrev_b32_e32 v21, 1, v41
	v_lshrrev_b32_e32 v19, 1, v19
	v_and_or_b32 v22, v23, 8, v22
	v_bitop3_b32 v191, v21, v24, v18 bitop3:0xde
	v_lshlrev_b32_e32 v20, 6, v20
	v_and_b32_e32 v23, 48, v21
	v_lshlrev_b32_e32 v39, 8, v184
	s_add_i32 s69, 0, 0x18800
	v_lshl_or_b32 v48, s64, 7, v204
	v_xad_u32 v188, v48, v47, v39
	v_add_u32_e32 v42, 0, v191
	s_or_b32 s92, s79, s68
	s_cmpk_lt_u32 s92, 0xbf
	s_cselect_b64 s[48:49], -1, 0
	v_readlane_b32 s34, v255, 35
	s_mov_b64 s[56:57], -1
	s_and_b64 vcc, exec, s[48:49]
	v_lshlrev_b32_e32 v197, 2, v185
	s_waitcnt vmcnt(0)
	v_lshlrev_b32_e32 v6, 16, v0
	v_and_b32_e32 v0, 0xffff0000, v0
	v_lshlrev_b32_e32 v7, 16, v1
	v_and_b32_e32 v1, 0xffff0000, v1
	v_lshlrev_b32_e32 v8, 16, v2
	v_and_b32_e32 v2, 0xffff0000, v2
	v_lshlrev_b32_e32 v9, 16, v3
	v_and_b32_e32 v3, 0xffff0000, v3
	v_mul_f32_e32 v0, 0x3e38aa3b, v0
	v_mul_f32_e32 v1, 0x3e38aa3b, v1
	v_mul_f32_e32 v2, 0x3e38aa3b, v2
	v_mul_f32_e32 v3, 0x3e38aa3b, v3
	v_mul_f32_e32 v6, 0x3e38aa3b, v6
	v_mul_f32_e32 v7, 0x3e38aa3b, v7
	v_mul_f32_e32 v8, 0x3e38aa3b, v8
	v_mul_f32_e32 v9, 0x3e38aa3b, v9
	v_cvt_pk_bf16_f32 v128, v6, v0
	v_cvt_pk_bf16_f32 v129, v7, v1
	v_cvt_pk_bf16_f32 v130, v8, v2
	v_cvt_pk_bf16_f32 v131, v9, v3
	global_load_dwordx4 v[0:3], v[4:5], off offset:32
	s_waitcnt vmcnt(0)
	v_lshlrev_b32_e32 v6, 16, v0
	v_and_b32_e32 v0, 0xffff0000, v0
	v_lshlrev_b32_e32 v7, 16, v1
	v_and_b32_e32 v1, 0xffff0000, v1
	v_lshlrev_b32_e32 v8, 16, v2
	v_and_b32_e32 v2, 0xffff0000, v2
	v_lshlrev_b32_e32 v9, 16, v3
	v_and_b32_e32 v3, 0xffff0000, v3
	v_mul_f32_e32 v0, 0x3e38aa3b, v0
	v_mul_f32_e32 v1, 0x3e38aa3b, v1
	v_mul_f32_e32 v2, 0x3e38aa3b, v2
	v_mul_f32_e32 v3, 0x3e38aa3b, v3
	v_mul_f32_e32 v6, 0x3e38aa3b, v6
	v_mul_f32_e32 v7, 0x3e38aa3b, v7
	v_mul_f32_e32 v8, 0x3e38aa3b, v8
	v_mul_f32_e32 v9, 0x3e38aa3b, v9
	v_cvt_pk_bf16_f32 v132, v6, v0
	v_cvt_pk_bf16_f32 v133, v7, v1
	v_cvt_pk_bf16_f32 v134, v8, v2
	v_cvt_pk_bf16_f32 v135, v9, v3
	global_load_dwordx4 v[0:3], v[4:5], off offset:64
	s_waitcnt vmcnt(0)
	v_lshlrev_b32_e32 v6, 16, v0
	v_and_b32_e32 v0, 0xffff0000, v0
	v_lshlrev_b32_e32 v7, 16, v1
	v_and_b32_e32 v1, 0xffff0000, v1
	v_lshlrev_b32_e32 v8, 16, v2
	v_and_b32_e32 v2, 0xffff0000, v2
	v_lshlrev_b32_e32 v9, 16, v3
	v_and_b32_e32 v3, 0xffff0000, v3
	v_mul_f32_e32 v0, 0x3e38aa3b, v0
	v_mul_f32_e32 v1, 0x3e38aa3b, v1
	v_mul_f32_e32 v2, 0x3e38aa3b, v2
	v_mul_f32_e32 v3, 0x3e38aa3b, v3
	v_mul_f32_e32 v6, 0x3e38aa3b, v6
	v_mul_f32_e32 v7, 0x3e38aa3b, v7
	v_mul_f32_e32 v8, 0x3e38aa3b, v8
	v_mul_f32_e32 v9, 0x3e38aa3b, v9
	v_cvt_pk_bf16_f32 v136, v6, v0
	v_cvt_pk_bf16_f32 v137, v7, v1
	v_cvt_pk_bf16_f32 v138, v8, v2
	v_cvt_pk_bf16_f32 v139, v9, v3
	global_load_dwordx4 v[0:3], v[4:5], off offset:96
	v_mad_i64_i32 v[4:5], s[0:1], v38, s73, 0
	v_mad_i64_i32 v[6:7], s[0:1], v17, s73, 0
	v_or_b32_e32 v4, v4, v41
	v_or_b32_e32 v6, v6, v41
	v_lshlrev_b64 v[4:5], 1, v[4:5]
	v_lshlrev_b64 v[6:7], 1, v[6:7]
	v_lshl_add_u64 v[8:9], s[18:19], 0, v[4:5]
	v_lshl_add_u64 v[12:13], s[18:19], 0, v[6:7]
	v_lshl_add_u64 v[4:5], s[42:43], 0, v[4:5]
	v_lshl_add_u64 v[6:7], s[42:43], 0, v[6:7]
	v_lshlrev_b32_e32 v17, 8, v17
	v_bitop3_b32 v192, v21, v17, v18 bitop3:0xde
	v_or_b32_e32 v17, v19, v16
	v_lshrrev_b32_e32 v18, 1, v22
	v_lshlrev_b32_e32 v17, 9, v17
	v_or_b32_e32 v16, v18, v16
	v_lshlrev_b32_e32 v16, 9, v16
	v_or3_b32 v193, v17, v20, v23
	v_or3_b32 v194, v16, v20, v23
	v_add_u32_e32 v44, 0, v193
	v_mov_b32_e32 v16, s69
	v_add_u32_e32 v43, 0, v192
	v_add_u32_e32 v45, 0, v194
	s_waitcnt vmcnt(0)
	v_lshlrev_b32_e32 v10, 16, v0
	v_and_b32_e32 v0, 0xffff0000, v0
	v_lshlrev_b32_e32 v11, 16, v1
	v_and_b32_e32 v1, 0xffff0000, v1
	v_lshlrev_b32_e32 v14, 16, v2
	v_and_b32_e32 v2, 0xffff0000, v2
	v_lshlrev_b32_e32 v15, 16, v3
	v_and_b32_e32 v3, 0xffff0000, v3
	v_mul_f32_e32 v10, 0x3e38aa3b, v10
	v_mul_f32_e32 v0, 0x3e38aa3b, v0
	v_mul_f32_e32 v11, 0x3e38aa3b, v11
	v_mul_f32_e32 v1, 0x3e38aa3b, v1
	v_mul_f32_e32 v14, 0x3e38aa3b, v14
	v_mul_f32_e32 v2, 0x3e38aa3b, v2
	v_mul_f32_e32 v15, 0x3e38aa3b, v15
	v_mul_f32_e32 v3, 0x3e38aa3b, v3
	v_cvt_pk_bf16_f32 v140, v10, v0
	v_cvt_pk_bf16_f32 v141, v11, v1
	v_cvt_pk_bf16_f32 v142, v14, v2
	v_cvt_pk_bf16_f32 v143, v15, v3
	global_load_dwordx4 v[0:3], v[4:5], off
	s_nop 0
	global_load_dwordx4 v[4:7], v[6:7], off
	s_nop 0
	global_load_dwordx4 v[8:11], v[8:9], off offset:2048
	s_nop 0
	global_load_dwordx4 v[12:15], v[12:13], off offset:2048
	s_waitcnt vmcnt(0)
	s_waitcnt vmcnt(3)
	ds_write_b128 v44, v[0:3]
	s_waitcnt vmcnt(2)
	ds_write_b128 v45, v[4:7]
	s_waitcnt vmcnt(1)
	ds_write_b128 v42, v[8:11] offset:16384
	s_waitcnt vmcnt(0)
	ds_write_b128 v43, v[12:15] offset:16384
	s_waitcnt lgkmcnt(0)
	s_barrier
; #define SETBE(t) do { TCLS(t); const float bt_ = near_ ? 0.f : ((rmax_ <= -128) ? bL : bR); \
;     if (bt_ != be_cur) { const float d_ = bt_ - be_cur; _Pragma("unroll") for (int r = 0; r < 16; ++r) negm[r] += d_; be_cur = bt_; } } while (0)
; template <int ND0> __device__ __forceinline__ void qkt(f32x16& p0, f32x16& p1, const char* Ks, const bf16x8* qr, int r32, int hi, int cboff, const f32x16& ci) {
; #pragma unroll
;   for (int d0 = 0; d0 < ND0; ++d0) { int cb = cboff + (d0 * 16 + hi * 8) * 2;
;     bf16x8 b0 = *reinterpret_cast<const bf16x8*>(Ks + KSWZ(r32, cb));
;     bf16x8 b1 = *reinterpret_cast<const bf16x8*>(Ks + KSWZ(32 + r32, cb));
;     if (d0 == 0) { p0 = __builtin_amdgcn_mfma_f32_32x32x16_bf16(b0, qr[0], ci, 0, 0, 0); p1 = __builtin_amdgcn_mfma_f32_32x32x16_bf16(b1, qr[0], ci, 0, 0, 0); }
;     else { p0 = __builtin_amdgcn_mfma_f32_32x32x16_bf16(b0, qr[d0], p0, 0, 0, 0); p1 = __builtin_amdgcn_mfma_f32_32x32x16_bf16(b1, qr[d0], p1, 0, 0, 0); } }
; }
; template <int MODE, int ORD> ...
;     ...
;   bL = tab[0]; bR = tab[256];
;   SETBE(0); qkt<ND0>(pA0, pA1, K_lds, qr, r32, hi, cboff, negm); BIAS(pA0, pA1, 0); partialSM2<MODE == 0>(pA0, pA1, m_reg, negm, alA);
	ds_read_b32 v195, v16
	v_add_u32_e32 v16, 0, v188
	ds_read_b128 v[34:37], v16 offset:16384
	v_bfrev_b32_e32 v0, 1
	s_waitcnt lgkmcnt(1)
	v_cndmask_b32_e64 v46, v195, 0, s[48:49]
	v_cmp_neq_f32_e64 s[0:1], 0, v46
	s_nop 1
	v_cndmask_b32_e64 v0, v0, v46, s[0:1]
	v_mov_b32_e32 v1, v0
	v_mov_b32_e32 v2, v0
	v_mov_b32_e32 v3, v0
	v_mov_b32_e32 v4, v0
	v_mov_b32_e32 v5, v0
	v_mov_b32_e32 v6, v0
	v_mov_b32_e32 v7, v0
	v_mov_b32_e32 v8, v0
	v_mov_b32_e32 v9, v0
	v_mov_b32_e32 v10, v0
	v_mov_b32_e32 v11, v0
	v_mov_b32_e32 v12, v0
	v_mov_b32_e32 v13, v0
	v_mov_b32_e32 v14, v0
	v_mov_b32_e32 v15, v0
	s_waitcnt lgkmcnt(0)
	s_nop 0
	v_mfma_f32_32x32x16_bf16 v[18:33], v[34:37], v[128:131], v[0:15]
	ds_read_b128 v[34:37], v16 offset:24576
	v_or_b32_e32 v16, 32, v48
	v_xad_u32 v196, v16, v47, v39
	v_mov_b64_e32 v[16:17], v[14:15]
	v_add_u32_e32 v49, 0, v196
	s_nop 1
	v_mov_b64_e32 v[14:15], v[12:13]
	v_mov_b64_e32 v[12:13], v[10:11]
	v_mov_b64_e32 v[10:11], v[8:9]
	v_mov_b64_e32 v[8:9], v[6:7]
	v_mov_b64_e32 v[6:7], v[4:5]
	v_mov_b64_e32 v[4:5], v[2:3]
	v_mov_b64_e32 v[2:3], v[0:1]
	v_or_b32_e32 v1, 64, v48
	v_xad_u32 v190, v1, v47, v39
	s_waitcnt lgkmcnt(0)
	v_mfma_f32_32x32x16_bf16 v[2:17], v[34:37], v[128:131], v[2:17]
	ds_read_b128 v[34:37], v49 offset:16384
	v_add_u32_e32 v1, 0, v190
	s_waitcnt lgkmcnt(0)
	v_mfma_f32_32x32x16_bf16 v[18:33], v[34:37], v[132:135], v[18:33]
	ds_read_b128 v[34:37], v49 offset:24576
	s_waitcnt lgkmcnt(0)
	v_mfma_f32_32x32x16_bf16 v[2:17], v[34:37], v[132:135], v[2:17]
	ds_read_b128 v[34:37], v1 offset:16384
	s_waitcnt lgkmcnt(0)
	v_mfma_f32_32x32x16_bf16 v[18:33], v[34:37], v[136:139], v[18:33]
	ds_read_b128 v[34:37], v1 offset:24576
	v_or_b32_e32 v1, 0x60, v48
	v_xad_u32 v189, v1, v47, v39
	v_add_u32_e32 v1, 0, v189
	s_waitcnt lgkmcnt(0)
	v_mfma_f32_32x32x16_bf16 v[2:17], v[34:37], v[136:139], v[2:17]
	ds_read_b128 v[34:37], v1 offset:16384
	s_waitcnt lgkmcnt(0)
	v_mfma_f32_32x32x16_bf16 v[18:33], v[34:37], v[140:143], v[18:33]
	ds_read_b128 v[34:37], v1 offset:24576
	v_mov_b32_e32 v1, s34
	ds_read_b32 v200, v1
	s_waitcnt lgkmcnt(1)
	v_mfma_f32_32x32x16_bf16 v[2:17], v[34:37], v[140:143], v[2:17]
	s_cbranch_vccnz .LBB0_159
	v_lshlrev_b32_e32 v1, 2, v185
	s_mov_b64 s[56:57], 0

; template <int MODE, int ORD> ...
;     ...
;   __syncthreads();
;   if (wid >= 4) __builtin_amdgcn_s_setprio(1);
; __global__ void __launch_bounds__(NWAVES * 64, 2) mega_fwd(Args args) {
;     ...
;             for (int U3 = vcu; U3 < 1280; U3 += G) {
;                 const int r = U3 >> 8, v = U3 & 255; const int w = v * 5 + r; const int rbk = w >> 3, hq = w & 7, kvh = hq >> 2;
;                 const size_t grow = (size_t)rbk * 256;
;                 const bool isP = grow < (size_t)M_P; const int S = isP ? SEQ_P : SEQ_S;
;                 const size_t row0 = isP ? (grow / SEQ_P) * SEQ_P : (size_t)M_P + ((grow - M_P) / SEQ_S) * SEQ_S;
;                 const int q0 = (int)(grow - row0);
;                 const int kb = q0 - 128 < 0 ? 0 : q0 - 128, ke = q0 + 384 > S ? S : q0 + 384;
.LBB0_209:
	s_and_b32 s1, s49, 0xff
	s_ashr_i32 s0, s49, 8
	s_mul_i32 s1, s1, 5
	s_add_i32 s1, s1, s0
	s_ashr_i32 s4, s1, 3
	s_ashr_i32 s5, s4, 31
	s_and_b32 s56, s1, 7
	s_lshl_b64 s[0:1], s[4:5], 8
	v_mov_b64_e32 v[0:1], 0x8000
	v_cmp_lt_u64_e32 vcc, s[0:1], v[0:1]
	s_and_b64 s[6:7], vcc, exec
	s_movk_i32 s6, 0xf000
	s_cselect_b32 s11, 0x2000, s77
	s_cselect_b32 s7, 0, -1
	s_cselect_b32 s6, 0x6000, s6
	s_or_b32 s64, s56, s48
	s_lshl_b64 s[18:19], s[64:65], 2
	s_add_u32 s18, s40, s18
	s_addc_u32 s19, s41, s19
	global_load_dword v2, v205, s[18:19]
	v_mov_b32_e32 v48, v244
	s_waitcnt vmcnt(63) expcnt(7) lgkmcnt(15)
	v_readfirstlane_b32 s10, v48
	s_ashr_i32 s42, s10, 6
	s_cmp_lt_i32 s42, 4
	s_barrier
	s_cbranch_scc1 .LBB0_211
	s_setprio 0
